# speedup vs baseline: 1.0024x; 1.0024x over previous
; template <class Epi, class Sched, bool FUSED = false, bool APERM = false>
; __device__ __forceinline__ void gemm_phase(int wid_s, LAS unsigned char* lds, const Gemm g, const Sched& S, const Epi& E) {
;     ...
;         const bool has_next = S.next(ui + 1, nxt);
;         const char* nA = has_next ? (const char*)g.A + (size_t)nxt.pm * tstep : cA; const char* nB = has_next ? (const char*)g.Bt + (size_t)nxt.pn * tstep : cB;
;     ...
; #pragma unroll
;         for (int a = 0; a < 2; ++a)
; #pragma unroll
;             for (int b = 0; b < 2; ++b)
; #pragma unroll
;                 for (int m = 0; m < 4; ++m)
; #pragma unroll
;                     for (int n = 0; n < 2; ++n) acc[a][b][m][n] = (f32x4){0.f, 0.f, 0.f, 0.f};
.LBB0_144:
	s_ashr_i32 s27, s26, 31
	s_lshl_b64 s[28:29], s[26:27], 20
	s_add_u32 s28, s47, s28
	s_addc_u32 s29, s48, s29
	s_and_b64 s[30:31], s[0:1], exec
	s_cselect_b32 s3, s29, s43
	s_cselect_b32 s10, s28, s42
	s_ashr_i32 s25, s24, 31
	s_lshl_b64 s[30:31], s[24:25], 20
	s_add_u32 s30, s49, s30
	s_addc_u32 s31, s50, s31
	s_and_b64 s[44:45], s[0:1], exec
	s_cselect_b32 s25, s31, s41
	s_cselect_b32 s27, s30, s40
	s_add_u32 s35, s40, 0x100
	s_addc_u32 s66, s41, 0
	s_add_u32 s40, s42, 0x80080
	v_mov_b32_e32 v8, 0
	s_addc_u32 s41, s43, 0
	s_mov_b32 s67, -2
	v_mov_b32_e32 v9, v8
	v_mov_b32_e32 v10, v8
	v_mov_b32_e32 v11, v8
	v_mov_b32_e32 v4, v8
	v_mov_b32_e32 v5, v8
	v_mov_b32_e32 v6, v8
	v_mov_b32_e32 v7, v8
	v_mov_b32_e32 v20, v8
	v_mov_b32_e32 v21, v8
	s_waitcnt vmcnt(0)
	v_mov_b64_e32 v[22:23], 0
	v_mov_b64_e32 v[24:25], 0
	v_mov_b64_e32 v[26:27], 0
	v_mov_b64_e32 v[36:37], 0
	v_mov_b64_e32 v[38:39], 0
	v_mov_b64_e32 v[40:41], 0
	v_mov_b64_e32 v[42:43], 0
	v_mov_b64_e32 v[52:53], 0
	v_mov_b64_e32 v[54:55], 0
	v_mov_b64_e32 v[56:57], 0
	v_mov_b64_e32 v[58:59], 0
	v_mov_b64_e32 v[16:17], 0
	v_mov_b64_e32 v[18:19], 0
	v_mov_b64_e32 v[12:13], 0
	v_mov_b64_e32 v[14:15], 0
	v_mov_b64_e32 v[28:29], 0
	v_mov_b64_e32 v[30:31], 0
	v_mov_b64_e32 v[32:33], 0
	v_mov_b64_e32 v[34:35], 0
	v_mov_b64_e32 v[44:45], 0
	v_mov_b64_e32 v[46:47], 0
	v_mov_b64_e32 v[48:49], 0
	v_mov_b64_e32 v[50:51], 0
	v_mov_b64_e32 v[60:61], 0
	v_mov_b64_e32 v[62:63], 0
	v_mov_b64_e32 v[64:65], 0
	v_mov_b64_e32 v[66:67], 0
	v_mov_b64_e32 v[72:73], 0
	v_mov_b64_e32 v[74:75], 0
	v_mov_b64_e32 v[68:69], 0
	v_mov_b64_e32 v[70:71], 0
	v_mov_b64_e32 v[84:85], 0
	v_mov_b64_e32 v[86:87], 0
	v_mov_b64_e32 v[88:89], 0
	v_mov_b64_e32 v[90:91], 0
	v_mov_b64_e32 v[100:101], 0
	v_mov_b64_e32 v[102:103], 0
	v_mov_b64_e32 v[104:105], 0
	v_mov_b64_e32 v[106:107], 0
	v_mov_b64_e32 v[116:117], 0
	v_mov_b64_e32 v[118:119], 0
	v_mov_b64_e32 v[120:121], 0
	v_mov_b64_e32 v[122:123], 0
	v_mov_b64_e32 v[76:77], 0
	v_mov_b64_e32 v[78:79], 0
	v_mov_b64_e32 v[80:81], 0
	v_mov_b64_e32 v[82:83], 0
	v_mov_b64_e32 v[92:93], 0
	v_mov_b64_e32 v[94:95], 0
	v_mov_b64_e32 v[96:97], 0
	v_mov_b64_e32 v[98:99], 0
	v_mov_b64_e32 v[108:109], 0
	v_mov_b64_e32 v[110:111], 0
	v_mov_b64_e32 v[112:113], 0
	v_mov_b64_e32 v[114:115], 0
	v_mov_b64_e32 v[124:125], 0
	v_mov_b64_e32 v[126:127], 0
	v_mov_b64_e32 v[128:129], 0
	v_mov_b64_e32 v[130:131], 0

; template <class Epi, class Sched, bool FUSED = false, bool APERM = false>
; __device__ __forceinline__ void gemm_phase(int wid_s, LAS unsigned char* lds, const Gemm g, const Sched& S, const Epi& E) {
;     ...
;         const bool has_next = S.next(ui + 1, nxt);
;         const char* nA = has_next ? (const char*)g.A + (size_t)nxt.pm * tstep : cA; const char* nB = has_next ? (const char*)g.Bt + (size_t)nxt.pn * tstep : cB;
;     ...
; #pragma unroll
;         for (int a = 0; a < 2; ++a)
; #pragma unroll
;             for (int b = 0; b < 2; ++b)
; #pragma unroll
;                 for (int m = 0; m < 4; ++m)
; #pragma unroll
;                     for (int n = 0; n < 2; ++n) acc[a][b][m][n] = (f32x4){0.f, 0.f, 0.f, 0.f};
.LBB0_341:
	s_ashr_i32 s23, s22, 31
	s_lshl_b64 s[28:29], s[22:23], 20
	s_add_u32 s28, s43, s28
	s_addc_u32 s29, s44, s29
	s_and_b64 s[30:31], s[26:27], exec
	s_cselect_b32 s1, s29, s39
	s_cselect_b32 s23, s28, s38
	s_ashr_i32 s25, s24, 31
	s_lshl_b64 s[30:31], s[24:25], 20
	s_add_u32 s30, s45, s30
	s_addc_u32 s31, s46, s31
	s_and_b64 s[40:41], s[26:27], exec
	s_cselect_b32 s25, s31, s37
	s_cselect_b32 s35, s30, s36
	s_add_u32 s61, s36, 0x100
	s_addc_u32 s62, s37, 0
	s_add_u32 s36, s38, 0x80080
	v_mov_b32_e32 v8, 0
	s_addc_u32 s37, s39, 0
	s_mov_b32 s63, -2
	v_mov_b32_e32 v9, v8
	v_mov_b64_e32 v[10:11], 0
	v_mov_b64_e32 v[4:5], 0
	v_mov_b64_e32 v[6:7], 0
	v_mov_b64_e32 v[20:21], 0
	v_mov_b64_e32 v[22:23], 0
	v_mov_b64_e32 v[24:25], 0
	v_mov_b64_e32 v[26:27], 0
	v_mov_b64_e32 v[36:37], 0
	v_mov_b64_e32 v[38:39], 0
	v_mov_b64_e32 v[40:41], 0
	v_mov_b64_e32 v[42:43], 0
	v_mov_b64_e32 v[52:53], 0
	v_mov_b64_e32 v[54:55], 0
	v_mov_b64_e32 v[56:57], 0
	v_mov_b64_e32 v[58:59], 0
	v_mov_b64_e32 v[16:17], 0
	v_mov_b64_e32 v[18:19], 0
	v_mov_b64_e32 v[12:13], 0
	v_mov_b64_e32 v[14:15], 0
	v_mov_b64_e32 v[28:29], 0
	v_mov_b64_e32 v[30:31], 0
	v_mov_b64_e32 v[32:33], 0
	v_mov_b64_e32 v[34:35], 0
	v_mov_b64_e32 v[44:45], 0
	v_mov_b64_e32 v[46:47], 0
	v_mov_b64_e32 v[48:49], 0
	v_mov_b64_e32 v[50:51], 0
	v_mov_b64_e32 v[60:61], 0
	v_mov_b64_e32 v[62:63], 0
	v_mov_b64_e32 v[64:65], 0
	v_mov_b64_e32 v[66:67], 0
	v_mov_b64_e32 v[72:73], 0
	v_mov_b64_e32 v[74:75], 0
	v_mov_b64_e32 v[68:69], 0
	v_mov_b64_e32 v[70:71], 0
	v_mov_b64_e32 v[84:85], 0
	v_mov_b64_e32 v[86:87], 0
	v_mov_b64_e32 v[88:89], 0
	v_mov_b64_e32 v[90:91], 0
	v_mov_b64_e32 v[100:101], 0
	v_mov_b64_e32 v[102:103], 0
	v_mov_b64_e32 v[104:105], 0
	v_mov_b64_e32 v[106:107], 0
	v_mov_b64_e32 v[116:117], 0
	v_mov_b64_e32 v[118:119], 0
	v_mov_b64_e32 v[120:121], 0
	v_mov_b64_e32 v[122:123], 0
	v_mov_b64_e32 v[76:77], 0
	v_mov_b64_e32 v[78:79], 0
	v_mov_b64_e32 v[80:81], 0
	v_mov_b64_e32 v[82:83], 0
	v_mov_b64_e32 v[92:93], 0
	v_mov_b64_e32 v[94:95], 0
	v_mov_b64_e32 v[96:97], 0
	v_mov_b64_e32 v[98:99], 0
	v_mov_b64_e32 v[108:109], 0
	v_mov_b64_e32 v[110:111], 0
	v_mov_b64_e32 v[112:113], 0
	v_mov_b64_e32 v[114:115], 0
	v_mov_b64_e32 v[124:125], 0
	v_mov_b64_e32 v[126:127], 0
	v_mov_b64_e32 v[128:129], 0
	v_mov_b64_e32 v[130:131], 0

; template <class Epi, class Sched, bool FUSED = false, bool APERM = false>
; __device__ __forceinline__ void gemm_phase(int wid_s, LAS unsigned char* lds, const Gemm g, const Sched& S, const Epi& E) {
;     ...
;         const bool has_next = S.next(ui + 1, nxt);
;         const char* nA = has_next ? (const char*)g.A + (size_t)nxt.pm * tstep : cA; const char* nB = has_next ? (const char*)g.Bt + (size_t)nxt.pn * tstep : cB;
;     ...
; #pragma unroll
;         for (int a = 0; a < 2; ++a)
; #pragma unroll
;             for (int b = 0; b < 2; ++b)
; #pragma unroll
;                 for (int m = 0; m < 4; ++m)
; #pragma unroll
;                     for (int n = 0; n < 2; ++n) acc[a][b][m][n] = (f32x4){0.f, 0.f, 0.f, 0.f};
.LBB0_581:
	s_ashr_i32 s15, s14, 31
	s_lshl_b64 s[16:17], s[14:15], 18
	s_add_u32 s16, s30, s16
	s_addc_u32 s17, s31, s17
	s_and_b64 s[18:19], s[0:1], exec
	s_cselect_b32 s15, s17, s25
	s_cselect_b32 s45, s16, s24
	s_ashr_i32 s9, s8, 31
	s_lshl_b64 s[18:19], s[8:9], 18
	s_add_u32 s18, s34, s18
	s_addc_u32 s19, s35, s19
	s_and_b64 s[26:27], s[0:1], exec
	s_cselect_b32 s9, s19, s23
	s_cselect_b32 s46, s18, s22
	s_add_u32 s47, s22, 0x100
	s_addc_u32 s48, s23, 0
	s_add_u32 s22, s24, 0x20080
	v_mov_b32_e32 v4, 0
	s_addc_u32 s23, s25, 0
	s_mov_b32 s49, -2
	v_mov_b32_e32 v5, v4
	v_mov_b64_e32 v[6:7], 0
	v_mov_b64_e32 v[12:13], 0
	v_mov_b64_e32 v[14:15], 0
	v_mov_b64_e32 v[20:21], 0
	v_mov_b64_e32 v[22:23], 0
	v_mov_b64_e32 v[28:29], 0
	v_mov_b64_e32 v[30:31], 0
	v_mov_b64_e32 v[36:37], 0
	v_mov_b64_e32 v[38:39], 0
	v_mov_b64_e32 v[44:45], 0
	v_mov_b64_e32 v[46:47], 0
	v_mov_b64_e32 v[52:53], 0
	v_mov_b64_e32 v[54:55], 0
	v_mov_b64_e32 v[60:61], 0
	v_mov_b64_e32 v[62:63], 0
	v_mov_b64_e32 v[8:9], 0
	v_mov_b64_e32 v[10:11], 0
	v_mov_b64_e32 v[16:17], 0
	v_mov_b64_e32 v[18:19], 0
	v_mov_b64_e32 v[24:25], 0
	v_mov_b64_e32 v[26:27], 0
	v_mov_b64_e32 v[32:33], 0
	v_mov_b64_e32 v[34:35], 0
	v_mov_b64_e32 v[40:41], 0
	v_mov_b64_e32 v[42:43], 0
	v_mov_b64_e32 v[48:49], 0
	v_mov_b64_e32 v[50:51], 0
	v_mov_b64_e32 v[56:57], 0
	v_mov_b64_e32 v[58:59], 0
	v_mov_b64_e32 v[64:65], 0
	v_mov_b64_e32 v[66:67], 0
	v_mov_b64_e32 v[68:69], 0
	v_mov_b64_e32 v[70:71], 0
	v_mov_b64_e32 v[76:77], 0
	v_mov_b64_e32 v[78:79], 0
	v_mov_b64_e32 v[84:85], 0
	v_mov_b64_e32 v[86:87], 0
	v_mov_b64_e32 v[92:93], 0
	v_mov_b64_e32 v[94:95], 0
	v_mov_b64_e32 v[100:101], 0
	v_mov_b64_e32 v[102:103], 0
	v_mov_b64_e32 v[108:109], 0
	v_mov_b64_e32 v[110:111], 0
	v_mov_b64_e32 v[116:117], 0
	v_mov_b64_e32 v[118:119], 0
	v_mov_b64_e32 v[124:125], 0
	v_mov_b64_e32 v[126:127], 0
	v_mov_b64_e32 v[72:73], 0
	v_mov_b64_e32 v[74:75], 0
	v_mov_b64_e32 v[80:81], 0
	v_mov_b64_e32 v[82:83], 0
	v_mov_b64_e32 v[88:89], 0
	v_mov_b64_e32 v[90:91], 0
	v_mov_b64_e32 v[96:97], 0
	v_mov_b64_e32 v[98:99], 0
	v_mov_b64_e32 v[104:105], 0
	v_mov_b64_e32 v[106:107], 0
	v_mov_b64_e32 v[112:113], 0
	v_mov_b64_e32 v[114:115], 0
	v_mov_b64_e32 v[120:121], 0
	v_mov_b64_e32 v[122:123], 0
	v_mov_b64_e32 v[128:129], 0
	v_mov_b64_e32 v[130:131], 0

; #define PG8_STAGE(bufoff, gbase, voff) do { _Pragma("unroll") for (int _i = 0; _i < 2; ++_i) \
;         __builtin_amdgcn_global_load_lds((const unsigned*)((const char*)(gbase) + (voff)[_i]), (LAS unsigned*)(lds + (bufoff) + ldsw + _i * 8192), 16, 0, 0); } while (0)
; #define PG8_WAIT_V(n) asm volatile("s_waitcnt vmcnt(" #n ")" ::: "memory")
; #define PG8_BAR __builtin_amdgcn_s_barrier()
; template <class Epi, class Sched, bool FUSED = false, bool APERM = false>
; __device__ __forceinline__ void gemm_phase(int wid_s, LAS unsigned char* lds, const Gemm g, const Sched& S, const Epi& E) {
;     ...
;     f32x4 acc[2][2][4][2];
; #pragma unroll
;     for (int a = 0; a < 2; ++a)
; #pragma unroll
;         for (int b = 0; b < 2; ++b)
; #pragma unroll
;             for (int m = 0; m < 4; ++m)
; #pragma unroll
;                 for (int n = 0; n < 2; ++n) acc[a][b][m][n] = (f32x4){0.f, 0.f, 0.f, 0.f};
;     bf16x8 At[4][2], B0[2][2], B1[2][2];
;     const char* cA = (const char*)g.A + (size_t)cur.pm * tstep; const char* cB = (const char*)g.Bt + (size_t)cur.pn * tstep;
;     S.a_ready(cur);
;     PG8_STAGE(PG8_SB(0, 0), cB, voffB); PG8_STAGE(PG8_SB(0, 1), cB + hstep, voffB); PG8_STAGE(PG8_SA(0, 0), cA, voffA); PG8_STAGE(PG8_SA(0, 1), cA + hstep, voffA);
;     if (wr == 1) PG8_BAR;
;     PG8_WAIT_V(2); PG8_BAR;
;     PG8_STAGE(PG8_SB(1, 0), cB + kstep, voffB); PG8_STAGE(PG8_SA(1, 0), cA + kstep, voffA); PG8_STAGE(PG8_SB(1, 1), cB + hstep + kstep, voffB);
;     PG8_WAIT_V(6); PG8_BAR;
.LBB0_645:
	v_bfe_u32 v220, v3, 4, 2
	v_and_b32_e32 v221, 15, v3
	v_lshlrev_b32_e32 v20, 4, v220
	v_lshlrev_b32_e32 v3, 2, v3
	s_sext_i32_i8 s16, s0
	s_and_b32 s10, s17, 3
	v_lshl_or_b32 v20, v221, 6, v20
	s_lshl_b32 s0, s1, 13
	v_and_b32_e32 v3, 32, v3
	s_add_i32 m0, s15, 0x18000
	v_lshl_add_u64 v[10:11], v[10:11], 0, s[12:13]
	s_lshl_b32 s53, s1, 6
	v_bitop3_b32 v21, v20, s0, v3 bitop3:0xde
	s_lshl_b32 s0, s10, 12
	s_waitcnt vmcnt(2)
	s_barrier
	global_load_lds_dwordx4 v[10:11], off
	v_lshl_add_u64 v[8:9], v[8:9], 0, s[12:13]
	s_add_i32 m0, s15, 0x1a000
	s_add_i32 s54, s15, 0x8000
	s_add_i32 s55, s15, 0xa000
	v_bitop3_b32 v3, v20, s0, v3 bitop3:0xde
	global_load_lds_dwordx4 v[8:9], off
	v_lshl_add_u64 v[4:5], v[4:5], 0, s[12:13]
	s_mov_b32 m0, s54
	s_add_u32 s0, s36, 0x80080
	global_load_lds_dwordx4 v[4:5], off
	v_lshl_add_u64 v[4:5], v[6:7], 0, s[12:13]
	s_mov_b32 m0, s55
	s_addc_u32 s1, s37, 0
	global_load_lds_dwordx4 v[4:5], off
	s_add_i32 m0, s15, 0x1c000
	v_lshl_add_u64 v[4:5], s[0:1], 0, v[0:1]
	global_load_lds_dwordx4 v[4:5], off
	v_lshl_add_u64 v[4:5], s[0:1], 0, v[132:133]
	s_add_i32 m0, s15, 0x1e000
	s_cmpk_lt_u32 s42, 0x100
	global_load_lds_dwordx4 v[4:5], off
	v_lshlrev_b32_e32 v4, 14, v16
	v_and_b32_e32 v4, 0x7fff8000, v4
	v_lshl_add_u32 v4, v17, 11, v4
	v_or_b32_e32 v4, v4, v18
	v_add_lshl_u32 v134, v4, v19, 1
	v_lshlrev_b32_e32 v4, 14, v12
	v_and_b32_e32 v4, 0x7fff8000, v4
	v_lshl_add_u32 v4, v13, 11, v4
	s_waitcnt vmcnt(6)
	v_or_b32_e32 v4, v4, v14
	v_add_lshl_u32 v136, v4, v15, 1
	v_mov_b32_e32 v4, 0
	s_cselect_b64 s[22:23], -1, 0
	v_mov_b32_e32 v135, v2
	v_mov_b32_e32 v137, v2
	s_mov_b32 s57, 0
	v_add_u32_e32 v142, 0, v21
	v_mov_b32_e32 v5, v4
	v_mov_b64_e32 v[6:7], 0
	v_mov_b64_e32 v[8:9], 0
	v_mov_b64_e32 v[10:11], 0
	v_mov_b64_e32 v[20:21], 0
	v_mov_b64_e32 v[22:23], 0
	v_mov_b64_e32 v[24:25], 0
	v_mov_b64_e32 v[26:27], 0
	v_mov_b64_e32 v[36:37], 0
	v_mov_b64_e32 v[38:39], 0
	v_mov_b64_e32 v[40:41], 0
	v_mov_b64_e32 v[42:43], 0
	v_mov_b64_e32 v[52:53], 0
	v_mov_b64_e32 v[54:55], 0
	v_mov_b64_e32 v[56:57], 0
	v_mov_b64_e32 v[58:59], 0
	v_mov_b64_e32 v[12:13], 0
	v_mov_b64_e32 v[14:15], 0
	v_mov_b64_e32 v[16:17], 0
	v_mov_b64_e32 v[18:19], 0
	v_mov_b64_e32 v[28:29], 0
	v_mov_b64_e32 v[30:31], 0
	v_mov_b64_e32 v[32:33], 0
	v_mov_b64_e32 v[34:35], 0
	v_mov_b64_e32 v[44:45], 0
	v_mov_b64_e32 v[46:47], 0
	v_mov_b64_e32 v[48:49], 0
	v_mov_b64_e32 v[50:51], 0
	v_mov_b64_e32 v[60:61], 0
	v_mov_b64_e32 v[62:63], 0
	v_mov_b64_e32 v[64:65], 0
	v_mov_b64_e32 v[66:67], 0
	v_mov_b64_e32 v[68:69], 0
	v_mov_b64_e32 v[70:71], 0
	v_mov_b64_e32 v[72:73], 0
	v_mov_b64_e32 v[74:75], 0
	v_mov_b64_e32 v[84:85], 0
	v_mov_b64_e32 v[86:87], 0
	v_mov_b64_e32 v[88:89], 0
	v_mov_b64_e32 v[90:91], 0
	v_mov_b64_e32 v[100:101], 0
	v_mov_b64_e32 v[102:103], 0
	v_mov_b64_e32 v[104:105], 0
	v_mov_b64_e32 v[106:107], 0
	v_mov_b64_e32 v[116:117], 0
	v_mov_b64_e32 v[118:119], 0
	v_mov_b64_e32 v[120:121], 0
	v_mov_b64_e32 v[122:123], 0
	v_mov_b64_e32 v[76:77], 0
	v_mov_b64_e32 v[78:79], 0
	v_mov_b64_e32 v[80:81], 0
	v_mov_b64_e32 v[82:83], 0
	v_mov_b64_e32 v[92:93], 0
	v_mov_b64_e32 v[94:95], 0
	v_mov_b64_e32 v[96:97], 0
	v_mov_b64_e32 v[98:99], 0
	v_mov_b64_e32 v[108:109], 0
	v_mov_b64_e32 v[110:111], 0
	v_mov_b64_e32 v[112:113], 0
	v_mov_b64_e32 v[114:115], 0
	v_mov_b64_e32 v[124:125], 0
	v_mov_b64_e32 v[126:127], 0
	v_mov_b64_e32 v[128:129], 0
	v_mov_b64_e32 v[130:131], 0
	s_barrier

; template <class Epi, class Sched, bool FUSED = false, bool APERM = false>
; __device__ __forceinline__ void gemm_phase(int wid_s, LAS unsigned char* lds, const Gemm g, const Sched& S, const Epi& E) {
;     ...
; #pragma unroll
;         for (int a = 0; a < 2; ++a)
; #pragma unroll
;             for (int b = 0; b < 2; ++b)
; #pragma unroll
;                 for (int m = 0; m < 4; ++m)
; #pragma unroll
;                     for (int n = 0; n < 2; ++n) acc[a][b][m][n] = (f32x4){0.f, 0.f, 0.f, 0.f};
;         cur = nxt; cA = nA; cB = nB; ++ui;
.LBB0_659:
	v_mov_b32_e32 v4, 0
	s_mov_b32 s16, s24
	s_mov_b32 s14, s26
	v_mov_b32_e32 v5, v4
	v_mov_b64_e32 v[6:7], 0
	v_mov_b64_e32 v[8:9], 0
	v_mov_b64_e32 v[10:11], 0
	v_mov_b64_e32 v[20:21], 0
	v_mov_b64_e32 v[22:23], 0
	v_mov_b64_e32 v[24:25], 0
	v_mov_b64_e32 v[26:27], 0
	v_mov_b64_e32 v[36:37], 0
	v_mov_b64_e32 v[38:39], 0
	v_mov_b64_e32 v[40:41], 0
	v_mov_b64_e32 v[42:43], 0
	v_mov_b64_e32 v[52:53], 0
	v_mov_b64_e32 v[54:55], 0
	v_mov_b64_e32 v[56:57], 0
	v_mov_b64_e32 v[58:59], 0
	v_mov_b64_e32 v[12:13], 0
	v_mov_b64_e32 v[14:15], 0
	v_mov_b64_e32 v[16:17], 0
	v_mov_b64_e32 v[18:19], 0
	v_mov_b64_e32 v[28:29], 0
	v_mov_b64_e32 v[30:31], 0
	v_mov_b64_e32 v[32:33], 0
	v_mov_b64_e32 v[34:35], 0
	v_mov_b64_e32 v[44:45], 0
	v_mov_b64_e32 v[46:47], 0
	v_mov_b64_e32 v[48:49], 0
	v_mov_b64_e32 v[50:51], 0
	v_mov_b64_e32 v[60:61], 0
	v_mov_b64_e32 v[62:63], 0
	v_mov_b64_e32 v[64:65], 0
	v_mov_b64_e32 v[66:67], 0
	v_mov_b64_e32 v[68:69], 0
	v_mov_b64_e32 v[70:71], 0
	v_mov_b64_e32 v[72:73], 0
	v_mov_b64_e32 v[74:75], 0
	v_mov_b64_e32 v[84:85], 0
	v_mov_b64_e32 v[86:87], 0
	v_mov_b64_e32 v[88:89], 0
	v_mov_b64_e32 v[90:91], 0
	v_mov_b64_e32 v[100:101], 0
	v_mov_b64_e32 v[102:103], 0
	v_mov_b64_e32 v[104:105], 0
	v_mov_b64_e32 v[106:107], 0
	v_mov_b64_e32 v[116:117], 0
	v_mov_b64_e32 v[118:119], 0
	v_mov_b64_e32 v[120:121], 0
	v_mov_b64_e32 v[122:123], 0
	v_mov_b64_e32 v[76:77], 0
	v_mov_b64_e32 v[78:79], 0
	v_mov_b64_e32 v[80:81], 0
	v_mov_b64_e32 v[82:83], 0
	v_mov_b64_e32 v[92:93], 0
	v_mov_b64_e32 v[94:95], 0
	v_mov_b64_e32 v[96:97], 0
	v_mov_b64_e32 v[98:99], 0
	v_mov_b64_e32 v[108:109], 0
	v_mov_b64_e32 v[110:111], 0
	v_mov_b64_e32 v[112:113], 0
	v_mov_b64_e32 v[114:115], 0
	v_mov_b64_e32 v[124:125], 0
	v_mov_b64_e32 v[126:127], 0
	v_mov_b64_e32 v[128:129], 0
	v_mov_b64_e32 v[130:131], 0
	s_andn2_b64 vcc, exec, s[0:1]
	s_cbranch_vccnz .LBB0_661
	s_branch .LBB0_662

; template <class Epi, class Sched, bool FUSED = false, bool APERM = false>
; __device__ __forceinline__ void gemm_phase(int wid_s, LAS unsigned char* lds, const Gemm g, const Sched& S, const Epi& E) {
;     ...
;         const bool has_next = S.next(ui + 1, nxt);
;         const char* nA = has_next ? (const char*)g.A + (size_t)nxt.pm * tstep : cA; const char* nB = has_next ? (const char*)g.Bt + (size_t)nxt.pn * tstep : cB;
;     ...
; #pragma unroll
;         for (int a = 0; a < 2; ++a)
; #pragma unroll
;             for (int b = 0; b < 2; ++b)
; #pragma unroll
;                 for (int m = 0; m < 4; ++m)
; #pragma unroll
;                     for (int n = 0; n < 2; ++n) acc[a][b][m][n] = (f32x4){0.f, 0.f, 0.f, 0.f};
.LBB0_753:
	s_ashr_i32 s29, s28, 31
	s_lshl_b64 s[30:31], s[28:29], 20
	s_add_u32 s30, s46, s30
	s_addc_u32 s31, s47, s31
	s_and_b64 s[34:35], s[0:1], exec
	s_cselect_b32 s3, s31, s7
	s_cselect_b32 s5, s30, s6
	s_ashr_i32 s27, s26, 31
	s_lshl_b64 s[34:35], s[26:27], 20
	s_add_u32 s34, s48, s34
	s_addc_u32 s35, s49, s35
	s_and_b64 s[38:39], s[0:1], exec
	s_cselect_b32 s27, s35, s37
	s_cselect_b32 s29, s34, s36
	s_add_u32 s42, s36, 0x100
	v_mov_b32_e32 v12, 0
	s_addc_u32 s43, s37, 0
	s_mov_b32 s44, -2
	v_mov_b32_e32 v13, v12
	v_mov_b64_e32 v[14:15], 0
	v_mov_b64_e32 v[104:105], 0
	v_mov_b64_e32 v[106:107], 0
	v_mov_b64_e32 v[16:17], 0
	v_mov_b64_e32 v[18:19], 0
	v_mov_b64_e32 v[108:109], 0
	v_mov_b64_e32 v[110:111], 0
	v_mov_b64_e32 v[20:21], 0
	v_mov_b64_e32 v[22:23], 0
	v_mov_b64_e32 v[116:117], 0
	v_mov_b64_e32 v[118:119], 0
	v_mov_b64_e32 v[28:29], 0
	v_mov_b64_e32 v[30:31], 0
	v_mov_b64_e32 v[124:125], 0
	v_mov_b64_e32 v[126:127], 0
	v_mov_b64_e32 v[4:5], 0
	v_mov_b64_e32 v[6:7], 0
	v_mov_b64_e32 v[112:113], 0
	v_mov_b64_e32 v[114:115], 0
	v_mov_b64_e32 v[8:9], 0
	v_mov_b64_e32 v[10:11], 0
	v_mov_b64_e32 v[100:101], 0
	v_mov_b64_e32 v[102:103], 0
	v_mov_b64_e32 v[24:25], 0
	v_mov_b64_e32 v[26:27], 0
	v_mov_b64_e32 v[120:121], 0
	v_mov_b64_e32 v[122:123], 0
	v_mov_b64_e32 v[32:33], 0
	v_mov_b64_e32 v[34:35], 0
	v_mov_b64_e32 v[128:129], 0
	v_mov_b64_e32 v[130:131], 0
	v_mov_b64_e32 v[52:53], 0
	v_mov_b64_e32 v[54:55], 0
	v_mov_b64_e32 v[136:137], 0
	v_mov_b64_e32 v[138:139], 0
	v_mov_b64_e32 v[40:41], 0
	v_mov_b64_e32 v[42:43], 0
	v_mov_b64_e32 v[140:141], 0
	v_mov_b64_e32 v[142:143], 0
	v_mov_b64_e32 v[56:57], 0
	v_mov_b64_e32 v[58:59], 0
	v_mov_b64_e32 v[152:153], 0
	v_mov_b64_e32 v[154:155], 0
	v_mov_b64_e32 v[60:61], 0
	v_mov_b64_e32 v[62:63], 0
	v_mov_b64_e32 v[156:157], 0
	v_mov_b64_e32 v[158:159], 0
	v_mov_b64_e32 v[44:45], 0
	v_mov_b64_e32 v[46:47], 0
	v_mov_b64_e32 v[144:145], 0
	v_mov_b64_e32 v[146:147], 0
	v_mov_b64_e32 v[36:37], 0
	v_mov_b64_e32 v[38:39], 0
	v_mov_b64_e32 v[132:133], 0
	v_mov_b64_e32 v[134:135], 0
	v_mov_b64_e32 v[48:49], 0
	v_mov_b64_e32 v[50:51], 0
	v_mov_b64_e32 v[148:149], 0
	v_mov_b64_e32 v[150:151], 0
	v_mov_b64_e32 v[64:65], 0
	v_mov_b64_e32 v[66:67], 0
	v_mov_b64_e32 v[160:161], 0
	v_mov_b64_e32 v[162:163], 0

; #define PG8_STAGE(bufoff, gbase, voff) do { _Pragma("unroll") for (int _i = 0; _i < 2; ++_i) \
;         __builtin_amdgcn_global_load_lds((const unsigned*)((const char*)(gbase) + (voff)[_i]), (LAS unsigned*)(lds + (bufoff) + ldsw + _i * 8192), 16, 0, 0); } while (0)
; #define PG8_WAIT_V(n) asm volatile("s_waitcnt vmcnt(" #n ")" ::: "memory")
; #define PG8_BAR __builtin_amdgcn_s_barrier()
; template <class Epi, class Sched, bool FUSED = false, bool APERM = false>
; __device__ __forceinline__ void gemm_phase(int wid_s, LAS unsigned char* lds, const Gemm g, const Sched& S, const Epi& E) {
;     ...
;     f32x4 acc[2][2][4][2];
; #pragma unroll
;     for (int a = 0; a < 2; ++a)
; #pragma unroll
;         for (int b = 0; b < 2; ++b)
; #pragma unroll
;             for (int m = 0; m < 4; ++m)
; #pragma unroll
;                 for (int n = 0; n < 2; ++n) acc[a][b][m][n] = (f32x4){0.f, 0.f, 0.f, 0.f};
;     bf16x8 At[4][2], B0[2][2], B1[2][2];
;     const char* cA = (const char*)g.A + (size_t)cur.pm * tstep; const char* cB = (const char*)g.Bt + (size_t)cur.pn * tstep;
;     S.a_ready(cur);
;     PG8_STAGE(PG8_SB(0, 0), cB, voffB); PG8_STAGE(PG8_SB(0, 1), cB + hstep, voffB); PG8_STAGE(PG8_SA(0, 0), cA, voffA); PG8_STAGE(PG8_SA(0, 1), cA + hstep, voffA);
;     if (wr == 1) PG8_BAR;
;     PG8_WAIT_V(2); PG8_BAR;
;     PG8_STAGE(PG8_SB(1, 0), cB + kstep, voffB); PG8_STAGE(PG8_SA(1, 0), cA + kstep, voffA); PG8_STAGE(PG8_SB(1, 1), cB + hstep + kstep, voffB);
;     PG8_WAIT_V(6); PG8_BAR;
.LBB0_917:
	v_bfe_u32 v220, v3, 4, 2
	v_and_b32_e32 v221, 15, v3
	v_lshlrev_b32_e32 v20, 4, v220
	v_lshlrev_b32_e32 v3, 2, v3
	s_and_b32 s10, s21, 3
	s_lshl_b32 s53, s0, 6
	v_lshl_or_b32 v20, v221, 6, v20
	s_lshl_b32 s0, s0, 13
	v_and_b32_e32 v3, 32, v3
	s_add_i32 m0, s49, 0x18000
	v_lshl_add_u64 v[10:11], v[10:11], 0, s[12:13]
	v_bitop3_b32 v21, v20, s0, v3 bitop3:0xde
	s_lshl_b32 s0, s10, 12
	s_waitcnt vmcnt(2)
	s_barrier
	global_load_lds_dwordx4 v[10:11], off
	v_lshl_add_u64 v[8:9], v[8:9], 0, s[12:13]
	s_add_i32 m0, s49, 0x1a000
	s_add_i32 s54, s49, 0x8000
	s_add_i32 s55, s49, 0xa000
	v_bitop3_b32 v3, v20, s0, v3 bitop3:0xde
	global_load_lds_dwordx4 v[8:9], off
	v_lshl_add_u64 v[4:5], v[4:5], 0, s[12:13]
	s_mov_b32 m0, s54
	s_add_u32 s0, s34, 0x158080
	s_sext_i32_i8 s20, s1
	global_load_lds_dwordx4 v[4:5], off
	v_lshl_add_u64 v[4:5], v[6:7], 0, s[12:13]
	s_mov_b32 m0, s55
	s_addc_u32 s1, s35, 0
	global_load_lds_dwordx4 v[4:5], off
	s_add_i32 m0, s49, 0x1c000
	v_lshl_add_u64 v[4:5], s[0:1], 0, v[0:1]
	global_load_lds_dwordx4 v[4:5], off
	v_lshl_add_u64 v[4:5], s[0:1], 0, v[132:133]
	s_add_i32 m0, s49, 0x1e000
	s_movk_i32 s2, 0x1580
	global_load_lds_dwordx4 v[4:5], off
	v_lshrrev_b32_e32 v5, 1, v16
	v_mul_lo_u32 v4, v18, s2
	s_mov_b32 s3, 0x15800
	v_mad_u64_u32 v[4:5], s[0:1], v5, s3, v[4:5]
	v_or_b32_e32 v4, v4, v17
	v_add_lshl_u32 v134, v4, v19, 1
	v_lshrrev_b32_e32 v5, 1, v12
	v_mul_lo_u32 v4, v14, s2
	v_mad_u64_u32 v[4:5], s[0:1], v5, s3, v[4:5]
	s_waitcnt vmcnt(6)
	v_or_b32_e32 v4, v4, v13
	s_cmpk_lt_u32 s40, 0x100
	v_add_lshl_u32 v136, v4, v15, 1
	v_mov_b32_e32 v4, 0
	s_cselect_b64 s[26:27], -1, 0
	v_mov_b32_e32 v135, v2
	v_mov_b32_e32 v137, v2
	s_mov_b32 s59, 0
	v_add_u32_e32 v142, 0, v21
	v_mov_b32_e32 v5, v4
	v_mov_b64_e32 v[6:7], 0
	v_mov_b64_e32 v[8:9], 0
	v_mov_b64_e32 v[10:11], 0
	v_mov_b64_e32 v[20:21], 0
	v_mov_b64_e32 v[22:23], 0
	v_mov_b64_e32 v[24:25], 0
	v_mov_b64_e32 v[26:27], 0
	v_mov_b64_e32 v[36:37], 0
	v_mov_b64_e32 v[38:39], 0
	v_mov_b64_e32 v[40:41], 0
	v_mov_b64_e32 v[42:43], 0
	v_mov_b64_e32 v[52:53], 0
	v_mov_b64_e32 v[54:55], 0
	v_mov_b64_e32 v[56:57], 0
	v_mov_b64_e32 v[58:59], 0
	v_mov_b64_e32 v[12:13], 0
	v_mov_b64_e32 v[14:15], 0
	v_mov_b64_e32 v[16:17], 0
	v_mov_b64_e32 v[18:19], 0
	v_mov_b64_e32 v[28:29], 0
	v_mov_b64_e32 v[30:31], 0
	v_mov_b64_e32 v[32:33], 0
	v_mov_b64_e32 v[34:35], 0
	v_mov_b64_e32 v[44:45], 0
	v_mov_b64_e32 v[46:47], 0
	v_mov_b64_e32 v[48:49], 0
	v_mov_b64_e32 v[50:51], 0
	v_mov_b64_e32 v[60:61], 0
	v_mov_b64_e32 v[62:63], 0
	v_mov_b64_e32 v[64:65], 0
	v_mov_b64_e32 v[66:67], 0
	v_mov_b64_e32 v[68:69], 0
	v_mov_b64_e32 v[70:71], 0
	v_mov_b64_e32 v[72:73], 0
	v_mov_b64_e32 v[74:75], 0
	v_mov_b64_e32 v[84:85], 0
	v_mov_b64_e32 v[86:87], 0
	v_mov_b64_e32 v[88:89], 0
	v_mov_b64_e32 v[90:91], 0
	v_mov_b64_e32 v[100:101], 0
	v_mov_b64_e32 v[102:103], 0
	v_mov_b64_e32 v[104:105], 0
	v_mov_b64_e32 v[106:107], 0
	v_mov_b64_e32 v[116:117], 0
	v_mov_b64_e32 v[118:119], 0
	v_mov_b64_e32 v[120:121], 0
	v_mov_b64_e32 v[122:123], 0
	v_mov_b64_e32 v[76:77], 0
	v_mov_b64_e32 v[78:79], 0
	v_mov_b64_e32 v[80:81], 0
	v_mov_b64_e32 v[82:83], 0
	v_mov_b64_e32 v[92:93], 0
	v_mov_b64_e32 v[94:95], 0
	v_mov_b64_e32 v[96:97], 0
	v_mov_b64_e32 v[98:99], 0
	v_mov_b64_e32 v[108:109], 0
	v_mov_b64_e32 v[110:111], 0
	v_mov_b64_e32 v[112:113], 0
	v_mov_b64_e32 v[114:115], 0
	v_mov_b64_e32 v[124:125], 0
	v_mov_b64_e32 v[126:127], 0
	v_mov_b64_e32 v[128:129], 0
	v_mov_b64_e32 v[130:131], 0
	s_barrier

; template <class Epi, class Sched, bool FUSED = false, bool APERM = false>
; __device__ __forceinline__ void gemm_phase(int wid_s, LAS unsigned char* lds, const Gemm g, const Sched& S, const Epi& E) {
;     ...
; #pragma unroll
;         for (int a = 0; a < 2; ++a)
; #pragma unroll
;             for (int b = 0; b < 2; ++b)
; #pragma unroll
;                 for (int m = 0; m < 4; ++m)
; #pragma unroll
;                     for (int n = 0; n < 2; ++n) acc[a][b][m][n] = (f32x4){0.f, 0.f, 0.f, 0.f};
;         cur = nxt; cA = nA; cB = nB; ++ui;
.LBB0_935:
	v_mov_b32_e32 v4, 0
	s_mov_b32 s20, s56
	s_mov_b32 s41, s57
	v_mov_b32_e32 v5, v4
	v_mov_b64_e32 v[6:7], 0
	v_mov_b64_e32 v[8:9], 0
	v_mov_b64_e32 v[10:11], 0
	v_mov_b64_e32 v[20:21], 0
	v_mov_b64_e32 v[22:23], 0
	v_mov_b64_e32 v[24:25], 0
	v_mov_b64_e32 v[26:27], 0
	v_mov_b64_e32 v[36:37], 0
	v_mov_b64_e32 v[38:39], 0
	v_mov_b64_e32 v[40:41], 0
	v_mov_b64_e32 v[42:43], 0
	v_mov_b64_e32 v[52:53], 0
	v_mov_b64_e32 v[54:55], 0
	v_mov_b64_e32 v[56:57], 0
	v_mov_b64_e32 v[58:59], 0
	v_mov_b64_e32 v[12:13], 0
	v_mov_b64_e32 v[14:15], 0
	v_mov_b64_e32 v[16:17], 0
	v_mov_b64_e32 v[18:19], 0
	v_mov_b64_e32 v[28:29], 0
	v_mov_b64_e32 v[30:31], 0
	v_mov_b64_e32 v[32:33], 0
	v_mov_b64_e32 v[34:35], 0
	v_mov_b64_e32 v[44:45], 0
	v_mov_b64_e32 v[46:47], 0
	v_mov_b64_e32 v[48:49], 0
	v_mov_b64_e32 v[50:51], 0
	v_mov_b64_e32 v[60:61], 0
	v_mov_b64_e32 v[62:63], 0
	v_mov_b64_e32 v[64:65], 0
	v_mov_b64_e32 v[66:67], 0
	v_mov_b64_e32 v[68:69], 0
	v_mov_b64_e32 v[70:71], 0
	v_mov_b64_e32 v[72:73], 0
	v_mov_b64_e32 v[74:75], 0
	v_mov_b64_e32 v[84:85], 0
	v_mov_b64_e32 v[86:87], 0
	v_mov_b64_e32 v[88:89], 0
	v_mov_b64_e32 v[90:91], 0
	v_mov_b64_e32 v[100:101], 0
	v_mov_b64_e32 v[102:103], 0
	v_mov_b64_e32 v[104:105], 0
	v_mov_b64_e32 v[106:107], 0
	v_mov_b64_e32 v[116:117], 0
	v_mov_b64_e32 v[118:119], 0
	v_mov_b64_e32 v[120:121], 0
	v_mov_b64_e32 v[122:123], 0
	v_mov_b64_e32 v[76:77], 0
	v_mov_b64_e32 v[78:79], 0
	v_mov_b64_e32 v[80:81], 0
	v_mov_b64_e32 v[82:83], 0
	v_mov_b64_e32 v[92:93], 0
	v_mov_b64_e32 v[94:95], 0
	v_mov_b64_e32 v[96:97], 0
	v_mov_b64_e32 v[98:99], 0
	v_mov_b64_e32 v[108:109], 0
	v_mov_b64_e32 v[110:111], 0
	v_mov_b64_e32 v[112:113], 0
	v_mov_b64_e32 v[114:115], 0
	v_mov_b64_e32 v[124:125], 0
	v_mov_b64_e32 v[126:127], 0
	v_mov_b64_e32 v[128:129], 0
	v_mov_b64_e32 v[130:131], 0
	s_andn2_b64 vcc, exec, s[0:1]
	s_cbranch_vccnz .LBB0_937
	s_branch .LBB0_938
